# PEER u sweep: rotating wave per workgroup touches the next 2-MiB u slice at each phase start (L2 prefetch)
# baseline (speedup 1.0000x reference)
; #define LAS __attribute__((address_space(3)))
; __device__ __forceinline__ void peer_block(int tok0, float* X1, const unsigned short* X1B, const int* TKI, const float* TKS, __amdgpu_buffer_rsrc_t U8r, __amdgpu_buffer_rsrc_t V6, const float* USC, const float* VSC,
;                                            const float* finw, pw_ptr L, int lane) {
;     const int g = lane >> 3, m = lane & 7, g16 = 16 * g, lo16 = 16 * m, hi8 = NEXP * 128 + 8 * m;
; #pragma unroll
;     for (int t = 0; t < PT; ++t) {
;         const size_t tk = (size_t)(tok0 + t);
;         const size_t rk0 = ((size_t)(lane >> 4) * M + tk) * 16 + (lane & 15), rk1 = rk0 + (size_t)4 * M * 16;
;         *(LAS int*)(L + PW_REC + t * 512 + lane * 4) = TKI[rk0]; *(LAS int*)(L + PW_REC + t * 512 + 256 + lane * 4) = TKI[rk1];
;         *(LAS int*)(L + PW_ACT + t * 512 + lane * 4) = 0; *(LAS int*)(L + PW_ACT + t * 512 + 256 + lane * 4) = 0;
;         const v4u* xb = (const v4u*)(X1B + tk * D + 16 * lane); float ss = 0.f, am = 0.f; float xv[16];
; __global__ void __launch_bounds__(NWAVES * 64, 2) mk_fwd(Params P) {
;     ...
;     if (IN(5)) {
;         const int gw = vcu * NWAVES + wave, NGW = G * NWAVES;
;         const unsigned long long ub_ = (unsigned long long)(uintptr_t)U8, vb_ = (unsigned long long)(uintptr_t)V8;
;         const unsigned long long ubu_ = ((unsigned long long)(unsigned)__builtin_amdgcn_readfirstlane((int)(ub_ >> 32)) << 32) | (unsigned)__builtin_amdgcn_readfirstlane((int)ub_);
;         const unsigned long long vbu_ = ((unsigned long long)(unsigned)__builtin_amdgcn_readfirstlane((int)(vb_ >> 32)) << 32) | (unsigned)__builtin_amdgcn_readfirstlane((int)vb_);
;         const __amdgpu_buffer_rsrc_t U6r = __builtin_amdgcn_make_buffer_rsrc((void*)(uintptr_t)ubu_, 0, NEXP * 1024, 0x00020000), V6r = __builtin_amdgcn_make_buffer_rsrc((void*)(uintptr_t)vbu_, 0, NEXP * 768, 0x00020000);
;         pw_ptr L = (pw_ptr)((LAS char*)lds + wave * PW_BYTES);
;         for (int tok0 = gw * PT; tok0 < M; tok0 += NGW * PT) peer_block(tok0, P.out, X1B, TKI, TKS, U6r, V6r, USC, VSC, P.finw, L, lane);
.LBB0_675:
	s_cmp_lt_i32 s72, 6
	s_cselect_b64 s[0:1], -1, 0
	s_cmp_gt_i32 s73, 5
	s_cselect_b64 s[2:3], -1, 0
	s_and_b64 s[0:1], s[0:1], s[2:3]
	s_andn2_b64 vcc, exec, s[0:1]
	s_cbranch_vccnz .LBB0_745
	v_readlane_b32 s87, v252, 0
	v_readlane_b32 s84, v252, 9
	s_nop 3
	s_and_b32 s87, s87, 31
	s_lshl_b32 s87, s87, 16
	v_lshl_add_u32 v137, v193, 7, s87
	v_readlane_b32 s0, v252, 0
	s_lshl_b32 s0, s0, 3
	v_readlane_b32 s1, v252, 9
	s_add_i32 s0, s0, s1
	s_cmpk_gt_i32 s0, 0x1fff
	s_cbranch_scc1 .LBB0_745
	v_mov_b32_e32 v73, 0
	v_lshlrev_b32_e32 v4, 5, v193
	v_mov_b32_e32 v5, v73
	v_lshl_add_u64 v[76:77], s[20:21], 0, v[4:5]
	v_mbcnt_lo_u32_b32 v4, -1, 0
	v_mbcnt_hi_u32_b32 v4, -1, v4
	v_and_b32_e32 v9, 64, v4
	v_xor_b32_e32 v5, 16, v4
	v_add_u32_e32 v9, 64, v9
	v_cmp_lt_i32_e32 vcc, v5, v9
	v_lshlrev_b32_e32 v0, 1, v180
	v_and_b32_e32 v7, 0x70, v0
	v_cndmask_b32_e32 v5, v4, v5, vcc
	v_lshlrev_b32_e32 v88, 2, v5
	v_xor_b32_e32 v5, 32, v4
	v_lshrrev_b32_e32 v0, 4, v193
	v_cmp_lt_i32_e32 vcc, v5, v9
	v_mul_u32_u24_e32 v72, 0xc000, v0
	v_and_b32_e32 v0, 15, v180
	v_cndmask_b32_e32 v4, v4, v5, vcc
	v_lshlrev_b32_e32 v0, 2, v0
	v_mov_b32_e32 v1, v73
	v_lshlrev_b32_e32 v89, 2, v4
	v_and_b32_e32 v4, 2, v180
	v_and_b32_e32 v6, 7, v180
	v_lshl_add_u64 v[74:75], s[6:7], 0, v[0:1]
	v_cmp_eq_u32_e64 s[4:5], 0, v4
	v_and_b32_e32 v4, 1, v180
	v_lshl_add_u64 v[78:79], s[8:9], 0, v[0:1]
	v_mov_b32_e32 v0, 0x200000
	v_readlane_b32 s1, v252, 9
	v_lshlrev_b32_e32 v5, 3, v4
	v_bfe_u32 v9, v180, 1, 2
	v_lshl_or_b32 v92, v6, 3, v0
	v_and_b32_e32 v0, 8, v180
	s_mulk_i32 s1, 0x4840
	v_lshlrev_b32_e32 v2, 4, v193
	v_mov_b32_e32 v3, v73
	v_or3_b32 v10, v5, v9, v7
	v_cmp_eq_u32_e64 s[8:9], 0, v0
	v_and_b32_e32 v0, 56, v180
	s_mov_b32 s63, 0x20000
	s_add_i32 s33, s1, 0
	v_lshlrev_b32_e32 v8, 2, v193
	v_lshlrev_b32_e32 v90, 4, v6
	v_lshlrev_b32_e32 v91, 2, v7
	v_lshlrev_b32_e32 v10, 2, v10
	v_lshl_add_u64 v[80:81], s[56:57], 0, v[2:3]
	v_lshlrev_b32_e32 v82, 3, v193
	v_mov_b32_e32 v83, v73
	v_lshl_add_u64 v[86:87], s[54:55], 0, v[2:3]
	v_or3_b32 v1, v9, v7, v5
	v_mov_b32_e32 v3, 0xc00
	v_lshl_or_b32 v0, v6, 6, v0
	s_mov_b32 s62, 0x1000000
	s_and_b32 s61, s61, 0xffff
	s_mov_b32 s66, 0xc00000
	s_mov_b32 s67, s63
	s_and_b32 s65, s65, 0xffff
	s_mul_i32 s12, s0, 6
	s_waitcnt lgkmcnt(0)
	s_mov_b32 s42, 64
	v_cmp_eq_u32_e64 s[0:1], 0, v193
	v_cmp_gt_u32_e64 s[2:3], 4, v6
	v_cmp_eq_u32_e64 s[6:7], 0, v4
	v_lshl_add_u64 v[84:85], s[20:21], 0, v[82:83]
	s_mul_i32 s43, s90, 48
	v_or_b32_e32 v83, 0x200, v91
	v_lshl_or_b32 v93, v1, 2, v3
	v_add_u32_e32 v94, 0x1840, v90
	v_add_u32_e32 v95, 0x1840, v0
	v_add_u32_e32 v96, s33, v8
	s_mov_b32 s44, 0xda24260
	s_mov_b32 s45, 0x42fe0000
	s_mov_b32 s46, 0x40c0c00
	v_add_u32_e32 v97, s33, v2
	v_mov_b32_e32 v98, 0x358637bd
	s_mov_b32 s47, 0xf800000
	v_mov_b32_e32 v99, 0x260
	s_movk_i32 s48, 0x80
	s_mov_b32 s49, 0xe00000
	v_add_u32_e32 v100, s33, v10
	s_mov_b32 s50, 0x378e98ab
	s_mov_b32 s51, 0x3b7cd369
	s_mov_b32 s52, 0xbcc618b2
	s_mov_b32 s53, 0x3dda74e4
	s_mov_b32 s54, 0x3f228afd
	s_mov_b32 s55, 0x3e03c728
	s_mov_b32 s56, 0xbfb8aa3b
	s_mov_b32 s57, 0x42ce8ed0
	s_mov_b32 s58, 0xc2b17218
	v_mov_b32_e32 v101, 0x3ba10414
	s_brev_b32 s59, -2
	v_mov_b32_e32 v102, 0xb9c68948
	v_mov_b32_e32 v103, 0x7f800000
	s_branch .LBB0_679

; #define LAS __attribute__((address_space(3)))
; #define PB_RECS(rv, t, q) do { rv = *(const LAS recv_t*)(L + PW_REC + (t) * 512 + (g16 + NPB * (q)) * 4); } while (0)
; #define PB_LOADU(buf, T8, rv, soff) do { _Pragma("unroll") for (int i_ = 0; i_ < 4; ++i_) { \
;       int oa_; asm("v_mad_u32_u16 %0, %1, %2, %3" : "=v"(oa_) : "v"(rv[i_]), "s"(128), "v"(lo16)); \
;       buf[i_] = __builtin_bit_cast(v4u, __builtin_amdgcn_raw_buffer_load_b128(T8, oa_, soff, 0)); } } while (0)
; __device__ __forceinline__ int pb_u_part(const v4u (&buf)[4], const v4u& xq, int m) {
;     int d[4];
; #pragma unroll
;     for (int i = 0; i < 4; ++i) { int a = __builtin_amdgcn_sdot4((int)buf[i][0], (int)xq[0], 0, false); a = __builtin_amdgcn_sdot4((int)buf[i][1], (int)xq[1], a, false);
;         a = __builtin_amdgcn_sdot4((int)buf[i][2], (int)xq[2], a, false); d[i] = __builtin_amdgcn_sdot4((int)buf[i][3], (int)xq[3], a, false); }
; __device__ __forceinline__ void peer_block(int tok0, float* X1, const unsigned short* X1B, const int* TKI, const float* TKS, __amdgpu_buffer_rsrc_t U8r, __amdgpu_buffer_rsrc_t V6, const float* USC, const float* VSC,
;                                            const float* finw, pw_ptr L, int lane) {
;     ...
;         for (int it = 0; it < NSU * PT; ++it) {
;             const int c = it / PT, t = it - c * PT; const int soff = c * SLU;
;             const int itn = it + 1, cn = itn / PT, tn = itn - cn * PT;
;             int rq[4];
;             xq = *(const LAS v4u*)(L + PW_Y + t * 1024 + 128 * c + 16 * m);
; #pragma unroll
;             for (int q = 0; q < 4; ++q) {
;                 const int qa = q + NBU - 1;
;                 if (qa < 4) { PB_RECS(rv, t, qa); PB_LOADU(bu[qa % NBU], U8r, rv, soff); }
;                 else if (itn < NSU * PT) { PB_RECS(rv, tn, qa - 4); PB_LOADU(bu[qa % NBU], U8r, rv, cn * SLU); }
;                 rq[q] = pb_u_part(bu[q % NBU], xq, m);
;             }
;             LAS int* ap = (LAS int*)(L + PW_ACT + t * 512 + (g16 + 8 * (m & 1) + (m >> 1)) * 4);
;             ap[0] += (m & 1) ? rq[2] : rq[0]; ap[4] += (m & 1) ? rq[3] : rq[1];
.LBB0_692:
	s_mul_hi_u32 s68, s11, 0xaaaaaaab
	s_mul_hi_u32 s71, s41, 0xaaaaaaab
	s_lshr_b32 s68, s68, 2
	s_lshr_b32 s71, s71, 2
	s_mul_i32 s72, s71, 6
	s_sub_u32 s72, s41, s72
	s_and_b32 s73, s71, 7
	s_sub_u32 s73, s73, s84
	s_or_b32 s85, s72, s73
	s_add_i32 s86, s71, 1
	s_lshl_b32 s86, s86, 21
	s_mulk_i32 s68, 0xc00
	s_mul_i32 s74, s71, 0xc00
	s_mulk_i32 s71, 0x1780
	s_add_i32 s69, s33, s10
	s_add_i32 s70, s33, s40
	v_subrev_u32_e32 v16, s68, v83
	v_subrev_u32_e32 v18, s74, v91
	v_subrev_u32_e32 v19, s71, v94
	v_subrev_u32_e32 v17, s74, v93
	v_add_u32_e32 v28, s69, v19
	v_add_u32_e32 v46, s70, v16
	v_add_u32_e32 v24, s70, v18
	v_add_u32_e32 v131, s70, v17
	ds_read_b128 v[16:19], v24 offset:16
	ds_read_b128 v[20:23], v24 offset:32
	ds_read_b128 v[24:27], v24 offset:48
	ds_read_b128 v[28:31], v28
	ds_read_b128 v[46:49], v46
	ds_read2_b32 v[70:71], v131 offset1:4
	s_mul_i32 s72, s11, 0x55800
	s_add_i32 s73, s72, 0x7faa800
	v_mov_b32_e32 v45, 0
	v_mov_b32_e32 v116, 0
	v_mov_b32_e32 v117, 0
	v_mov_b32_e32 v118, 0
	s_and_b32 s73, s73, 0x7e00000
	s_waitcnt lgkmcnt(5)
	v_mad_u32_u16 v16, v16, s48, v90
	v_mad_u32_u16 v50, v17, s48, v90
	v_mad_u32_u16 v51, v18, s48, v90
	v_mad_u32_u16 v52, v19, s48, v90
	s_waitcnt lgkmcnt(3)
	v_mad_u32_u16 v66, v24, s48, v90
	v_mad_u32_u16 v104, v25, s48, v90
	v_mad_u32_u16 v108, v26, s48, v90
	v_mad_u32_u16 v112, v27, s48, v90
	s_waitcnt vmcnt(3) lgkmcnt(2)
	v_dot4c_i32_i8_e32 v45, v12, v28
	s_waitcnt vmcnt(2)
	v_dot4c_i32_i8_e32 v116, v8, v28
	s_waitcnt vmcnt(1)
	v_dot4c_i32_i8_e32 v117, v4, v28
	s_waitcnt vmcnt(0)
	v_dot4c_i32_i8_e32 v118, v0, v28
	v_mad_u32_u16 v0, v20, s48, v90
	v_mad_u32_u16 v4, v21, s48, v90
	v_mad_u32_u16 v8, v22, s48, v90
	v_mad_u32_u16 v12, v23, s48, v90
	s_waitcnt lgkmcnt(1)
	v_mad_u32_u16 v132, v46, s48, v90
	v_mad_u32_u16 v133, v47, s48, v90
	v_mad_u32_u16 v134, v48, s48, v90
	v_mad_u32_u16 v135, v49, s48, v90
	buffer_load_dwordx4 v[16:19], v16, s[60:63], s73 offen
	s_nop 0
	buffer_load_dwordx4 v[20:23], v50, s[60:63], s73 offen
	buffer_load_dwordx4 v[24:27], v51, s[60:63], s73 offen
	buffer_load_dwordx4 v[46:49], v52, s[60:63], s73 offen
	s_nop 0
	buffer_load_dwordx4 v[50:53], v0, s[60:63], s73 offen
	buffer_load_dwordx4 v[54:57], v4, s[60:63], s73 offen
	buffer_load_dwordx4 v[58:61], v8, s[60:63], s73 offen
	buffer_load_dwordx4 v[62:65], v12, s[60:63], s73 offen
	s_nop 0
	buffer_load_dwordx4 v[66:69], v66, s[60:63], s73 offen
	s_nop 0
	buffer_load_dwordx4 v[104:107], v104, s[60:63], s73 offen
	s_nop 0
	buffer_load_dwordx4 v[108:111], v108, s[60:63], s73 offen
	s_nop 0
	buffer_load_dwordx4 v[112:115], v112, s[60:63], s73 offen
	v_dot4c_i32_i8_e32 v45, v13, v29
	v_dot4c_i32_i8_e32 v116, v9, v29
	v_dot4c_i32_i8_e32 v117, v5, v29
	v_dot4c_i32_i8_e32 v118, v1, v29
	s_and_b32 s72, s72, 0x7e00000
	v_dot4c_i32_i8_e32 v45, v14, v30
	v_dot4c_i32_i8_e32 v116, v10, v30
	v_dot4c_i32_i8_e32 v117, v6, v30
	v_dot4c_i32_i8_e32 v118, v2, v30
	v_dot4c_i32_i8_e32 v45, v15, v31
	v_dot4c_i32_i8_e32 v116, v11, v31
	v_dot4c_i32_i8_e32 v117, v7, v31
	v_dot4c_i32_i8_e32 v118, v3, v31
	buffer_load_dwordx4 v[12:15], v132, s[60:63], s72 offen
	buffer_load_dwordx4 v[8:11], v133, s[60:63], s72 offen
	buffer_load_dwordx4 v[4:7], v134, s[60:63], s72 offen
	buffer_load_dwordx4 v[0:3], v135, s[60:63], s72 offen
	s_cmp_lg_u32 s85, 0
	s_cbranch_scc1 .Lpf_skip
	buffer_load_dword v136, v137, s[60:63], s86 offen
	s_add_i32 s86, s86, 0x2000
	buffer_load_dword v136, v137, s[60:63], s86 offen
	s_add_i32 s86, s86, 0x2000
	buffer_load_dword v136, v137, s[60:63], s86 offen
	s_add_i32 s86, s86, 0x2000
	buffer_load_dword v136, v137, s[60:63], s86 offen
	s_add_i32 s86, s86, 0x2000
	buffer_load_dword v136, v137, s[60:63], s86 offen
	s_add_i32 s86, s86, 0x2000
	buffer_load_dword v136, v137, s[60:63], s86 offen
	s_add_i32 s86, s86, 0x2000
	buffer_load_dword v136, v137, s[60:63], s86 offen
	s_add_i32 s86, s86, 0x2000
	buffer_load_dword v136, v137, s[60:63], s86 offen
.Lpf_skip:
	v_mov_b32_e32 v119, 0
	v_mov_b32_e32 v120, 0
	v_mov_b32_e32 v121, 0
	v_mov_b32_e32 v122, 0
	v_mov_b32_e32 v123, 0
	v_mov_b32_e32 v124, 0
	v_mov_b32_e32 v125, 0
	v_mov_b32_e32 v126, 0
	v_mov_b32_e32 v127, 0
	v_mov_b32_e32 v128, 0
	v_mov_b32_e32 v129, 0
	v_mov_b32_e32 v130, 0
	v_cndmask_b32_e64 v132, v117, v45, s[2:3]
	v_cndmask_b32_e64 v45, v45, v117, s[2:3]
	v_cndmask_b32_e64 v117, v118, v116, s[2:3]
	v_cndmask_b32_e64 v116, v116, v118, s[2:3]
	v_add_u32_dpp v45, v45, v132 row_half_mirror row_mask:0xf bank_mask:0xf bound_ctrl:1
	s_add_i32 s41, s41, 1
	v_add_u32_dpp v116, v116, v117 row_half_mirror row_mask:0xf bank_mask:0xf bound_ctrl:1
	v_cndmask_b32_e64 v117, v116, v45, s[4:5]
	v_cndmask_b32_e64 v45, v45, v116, s[4:5]
	s_add_i32 s11, s11, 1
	s_addk_i32 s40, 0x200
	v_add_u32_dpp v45, v45, v117 quad_perm:[2,3,0,1] row_mask:0xf bank_mask:0xf bound_ctrl:1
	s_addk_i32 s10, 0x400
	s_cmp_eq_u32 s11, 48
	v_add_u32_dpp v45, v45, v45 quad_perm:[1,0,3,2] row_mask:0xf bank_mask:0xf bound_ctrl:1
	s_waitcnt vmcnt(15)
	v_dot4c_i32_i8_e32 v119, v16, v28
	s_waitcnt vmcnt(14)
	v_dot4c_i32_i8_e32 v120, v20, v28
	s_waitcnt vmcnt(13)
	v_dot4c_i32_i8_e32 v121, v24, v28
	s_waitcnt vmcnt(12)
	v_dot4c_i32_i8_e32 v122, v46, v28
	s_waitcnt vmcnt(11)
	v_dot4c_i32_i8_e32 v123, v50, v28
	s_waitcnt vmcnt(10)
	v_dot4c_i32_i8_e32 v124, v54, v28
	s_waitcnt vmcnt(9)
	v_dot4c_i32_i8_e32 v125, v58, v28
	s_waitcnt vmcnt(8)
	v_dot4c_i32_i8_e32 v126, v62, v28
	s_waitcnt vmcnt(7)
	v_dot4c_i32_i8_e32 v127, v66, v28
	s_waitcnt vmcnt(6)
	v_dot4c_i32_i8_e32 v128, v104, v28
	s_waitcnt vmcnt(5)
	v_dot4c_i32_i8_e32 v129, v108, v28
	s_waitcnt vmcnt(4)
; __device__ __forceinline__ float row16_sum(float v) { v += dppf<0xB1>(v); v += dppf<0x4E>(v); v += dppf<0x141>(v); v += dppf<0x140>(v); return v; }
; #define LAS __attribute__((address_space(3)))
; __device__ __forceinline__ void peer_block(int tok0, float* X1, const unsigned short* X1B, const int* TKI, const float* TKS, __amdgpu_buffer_rsrc_t U8r, __amdgpu_buffer_rsrc_t V6, const float* USC, const float* VSC,
;                                            const float* finw, pw_ptr L, int lane) {
;     ...
;         for (int it = 0; it < NSU * PT; ++it) {
;             const int c = it / PT, t = it - c * PT; const int soff = c * SLU;
;             const int itn = it + 1, cn = itn / PT, tn = itn - cn * PT;
;             int rq[4];
;             xq = *(const LAS v4u*)(L + PW_Y + t * 1024 + 128 * c + 16 * m);
; #pragma unroll
;             for (int q = 0; q < 4; ++q) {
;                 const int qa = q + NBU - 1;
;                 if (qa < 4) { PB_RECS(rv, t, qa); PB_LOADU(bu[qa % NBU], U8r, rv, soff); }
;                 else if (itn < NSU * PT) { PB_RECS(rv, tn, qa - 4); PB_LOADU(bu[qa % NBU], U8r, rv, cn * SLU); }
;                 rq[q] = pb_u_part(bu[q % NBU], xq, m);
;             }
;             LAS int* ap = (LAS int*)(L + PW_ACT + t * 512 + (g16 + 8 * (m & 1) + (m >> 1)) * 4);
;             ap[0] += (m & 1) ? rq[2] : rq[0]; ap[4] += (m & 1) ? rq[3] : rq[1];
;         }
;     }
; #pragma unroll
;     for (int t = 0; t < PT; ++t) {
;         const size_t tk = (size_t)(tok0 + t);
;         const float r = *(const LAS float*)(L + PW_R + t * 8), rx = *(const LAS float*)(L + PW_R + t * 8 + 4);
;         const int i0 = *(const LAS int*)(L + PW_REC + t * 512 + lane * 4), i1 = *(const LAS int*)(L + PW_REC + t * 512 + 256 + lane * 4);
;         const size_t rk0 = ((size_t)(lane >> 4) * M + tk) * 16 + (lane & 15), rk1 = rk0 + (size_t)4 * M * 16;
;         const float s0 = TKS[rk0] * r, s1 = TKS[rk1] * r;
;         const float e0 = __expf(s0 - row16_max(s0)), e1 = __expf(s1 - row16_max(s1));
;         const float g0 = e0 / row16_sum(e0), g1 = e1 / row16_sum(e1);
;         const f32x2c sc0 = *(const f32x2c*)(USC + 2 * i0), sc1 = *(const f32x2c*)(USC + 2 * i1);
;         const float a0 = (float)*(const LAS int*)(L + PW_ACT + t * 512 + lane * 4) * rx * sc0.x, a1 = (float)*(const LAS int*)(L + PW_ACT + t * 512 + 256 + lane * 4) * rx * sc1.x;
	v_dot4c_i32_i8_e32 v130, v112, v28
	v_dot4c_i32_i8_e32 v119, v17, v29
	v_dot4c_i32_i8_e32 v120, v21, v29
	v_dot4c_i32_i8_e32 v121, v25, v29
	v_dot4c_i32_i8_e32 v122, v47, v29
	v_dot4c_i32_i8_e32 v123, v51, v29
	v_dot4c_i32_i8_e32 v124, v55, v29
	v_dot4c_i32_i8_e32 v125, v59, v29
	v_dot4c_i32_i8_e32 v126, v63, v29
	v_dot4c_i32_i8_e32 v127, v67, v29
	v_dot4c_i32_i8_e32 v128, v105, v29
	v_dot4c_i32_i8_e32 v129, v109, v29
	v_dot4c_i32_i8_e32 v130, v113, v29
	v_dot4c_i32_i8_e32 v119, v18, v30
	v_dot4c_i32_i8_e32 v120, v22, v30
	v_dot4c_i32_i8_e32 v121, v26, v30
	v_dot4c_i32_i8_e32 v122, v48, v30
	v_dot4c_i32_i8_e32 v123, v52, v30
	v_dot4c_i32_i8_e32 v124, v56, v30
	v_dot4c_i32_i8_e32 v125, v60, v30
	v_dot4c_i32_i8_e32 v126, v64, v30
	v_dot4c_i32_i8_e32 v127, v68, v30
	v_dot4c_i32_i8_e32 v128, v106, v30
	v_dot4c_i32_i8_e32 v129, v110, v30
	v_dot4c_i32_i8_e32 v130, v114, v30
	v_dot4c_i32_i8_e32 v119, v19, v31
	v_dot4c_i32_i8_e32 v120, v23, v31
	v_dot4c_i32_i8_e32 v121, v27, v31
	v_dot4c_i32_i8_e32 v122, v49, v31
	v_dot4c_i32_i8_e32 v123, v53, v31
	v_dot4c_i32_i8_e32 v124, v57, v31
	v_dot4c_i32_i8_e32 v125, v61, v31
	v_dot4c_i32_i8_e32 v126, v65, v31
	v_dot4c_i32_i8_e32 v127, v69, v31
	v_dot4c_i32_i8_e32 v128, v107, v31
	v_dot4c_i32_i8_e32 v129, v111, v31
	v_dot4c_i32_i8_e32 v130, v115, v31
	v_cndmask_b32_e64 v16, v121, v119, s[2:3]
	v_cndmask_b32_e64 v17, v119, v121, s[2:3]
	v_cndmask_b32_e64 v18, v122, v120, s[2:3]
	v_cndmask_b32_e64 v19, v120, v122, s[2:3]
	v_cndmask_b32_e64 v20, v125, v123, s[2:3]
	v_cndmask_b32_e64 v21, v123, v125, s[2:3]
	v_cndmask_b32_e64 v22, v126, v124, s[2:3]
	v_cndmask_b32_e64 v23, v124, v126, s[2:3]
	v_cndmask_b32_e64 v24, v129, v127, s[2:3]
	v_cndmask_b32_e64 v25, v127, v129, s[2:3]
	v_cndmask_b32_e64 v26, v130, v128, s[2:3]
	v_cndmask_b32_e64 v27, v128, v130, s[2:3]
	v_add_u32_dpp v16, v17, v16 row_half_mirror row_mask:0xf bank_mask:0xf bound_ctrl:1
	v_add_u32_dpp v17, v19, v18 row_half_mirror row_mask:0xf bank_mask:0xf bound_ctrl:1
	v_add_u32_dpp v18, v21, v20 row_half_mirror row_mask:0xf bank_mask:0xf bound_ctrl:1
	v_add_u32_dpp v19, v23, v22 row_half_mirror row_mask:0xf bank_mask:0xf bound_ctrl:1
	v_add_u32_dpp v20, v25, v24 row_half_mirror row_mask:0xf bank_mask:0xf bound_ctrl:1
	v_add_u32_dpp v21, v27, v26 row_half_mirror row_mask:0xf bank_mask:0xf bound_ctrl:1
	v_cndmask_b32_e64 v22, v17, v16, s[4:5]
	v_cndmask_b32_e64 v16, v16, v17, s[4:5]
	v_cndmask_b32_e64 v17, v19, v18, s[4:5]
	v_cndmask_b32_e64 v18, v18, v19, s[4:5]
	v_cndmask_b32_e64 v19, v21, v20, s[4:5]
	v_cndmask_b32_e64 v20, v20, v21, s[4:5]
	v_add_u32_dpp v16, v16, v22 quad_perm:[2,3,0,1] row_mask:0xf bank_mask:0xf bound_ctrl:1
	v_add_u32_dpp v17, v18, v17 quad_perm:[2,3,0,1] row_mask:0xf bank_mask:0xf bound_ctrl:1
	v_add_u32_dpp v18, v20, v19 quad_perm:[2,3,0,1] row_mask:0xf bank_mask:0xf bound_ctrl:1
	v_add_u32_dpp v16, v16, v16 quad_perm:[1,0,3,2] row_mask:0xf bank_mask:0xf bound_ctrl:1
	v_add_u32_dpp v17, v17, v17 quad_perm:[1,0,3,2] row_mask:0xf bank_mask:0xf bound_ctrl:1
	v_add_u32_dpp v18, v18, v18 quad_perm:[1,0,3,2] row_mask:0xf bank_mask:0xf bound_ctrl:1
	v_cndmask_b32_e64 v17, v17, v45, s[6:7]
	v_cndmask_b32_e64 v16, v18, v16, s[6:7]
	s_waitcnt lgkmcnt(0)
	v_add_u32_e32 v17, v70, v17
	v_add_u32_e32 v16, v71, v16
	ds_write2_b32 v131, v17, v16 offset1:4
	s_cbranch_scc0 .LBB0_692
	ds_read_b128 v[16:19], v44 offset:2576
	ds_read_b128 v[46:49], v44 offset:2592
	v_add_u32_e32 v45, s33, v90
	v_mov_b32_e32 v119, 0
	v_mov_b32_e32 v116, 0
	s_waitcnt lgkmcnt(1)
	v_mad_u32_u16 v16, v16, s48, v90
	v_mad_u32_u16 v20, v17, s48, v90
	v_mad_u32_u16 v24, v18, s48, v90
	v_mad_u32_u16 v28, v19, s48, v90
	buffer_load_dwordx4 v[16:19], v16, s[60:63], s49 offen
	s_nop 0
	buffer_load_dwordx4 v[20:23], v20, s[60:63], s49 offen
	s_nop 0
	buffer_load_dwordx4 v[24:27], v24, s[60:63], s49 offen
	s_nop 0
	buffer_load_dwordx4 v[28:31], v28, s[60:63], s49 offen
	s_waitcnt lgkmcnt(0)
	v_mad_u32_u16 v46, v46, s48, v90
	buffer_load_dwordx4 v[50:53], v46, s[60:63], s49 offen
	v_mad_u32_u16 v46, v47, s48, v90
	buffer_load_dwordx4 v[54:57], v46, s[60:63], s49 offen
	v_mad_u32_u16 v46, v48, s48, v90
	buffer_load_dwordx4 v[58:61], v46, s[60:63], s49 offen
	ds_read_b128 v[62:65], v45 offset:12224
	ds_read_b128 v[66:69], v44 offset:2608
	v_mad_u32_u16 v45, v49, s48, v90
	buffer_load_dwordx4 v[46:49], v45, s[60:63], s49 offen
	v_mov_b32_e32 v117, 0
	v_mov_b32_e32 v118, 0
	s_waitcnt vmcnt(8) lgkmcnt(1)
	v_dot4c_i32_i8_e32 v119, v0, v62
	s_waitcnt lgkmcnt(0)
	v_mad_u32_u16 v0, v66, s48, v90
	v_dot4c_i32_i8_e32 v116, v12, v62
	v_dot4c_i32_i8_e32 v117, v8, v62
	v_dot4c_i32_i8_e32 v118, v4, v62
	v_mad_u32_u16 v4, v67, s48, v90
	v_mad_u32_u16 v8, v68, s48, v90
	v_mad_u32_u16 v12, v69, s48, v90
	buffer_load_dwordx4 v[66:69], v0, s[60:63], s49 offen
	buffer_load_dwordx4 v[104:107], v4, s[60:63], s49 offen
	buffer_load_dwordx4 v[108:111], v8, s[60:63], s49 offen
	buffer_load_dwordx4 v[112:115], v12, s[60:63], s49 offen
	v_lshl_add_u64 v[40:41], v[78:79], 0, v[40:41]
	v_dot4c_i32_i8_e32 v117, v9, v63
	v_add_co_u32_e32 v70, vcc, s66, v40
	v_dot4c_i32_i8_e32 v117, v10, v64
	s_nop 0
	v_addc_co_u32_e32 v71, vcc, 0, v41, vcc
	v_dot4c_i32_i8_e32 v116, v13, v63
	v_dot4c_i32_i8_e32 v117, v11, v65
	global_load_dword v11, v[40:41], off
	global_load_dword v13, v[70:71], off
	v_dot4c_i32_i8_e32 v118, v5, v63
	v_dot4c_i32_i8_e32 v119, v1, v63
	v_dot4c_i32_i8_e32 v116, v14, v64
	v_dot4c_i32_i8_e32 v118, v6, v64
	v_dot4c_i32_i8_e32 v119, v2, v64
	v_mov_b32_e32 v120, 0
	v_mov_b32_e32 v121, 0
	v_mov_b32_e32 v122, 0
	v_mov_b32_e32 v123, 0
	v_dot4c_i32_i8_e32 v116, v15, v65
	v_dot4c_i32_i8_e32 v118, v7, v65
	v_dot4c_i32_i8_e32 v119, v3, v65
	v_mov_b32_e32 v124, 0
	v_mov_b32_e32 v8, 0
	v_cndmask_b32_e64 v0, v118, v116, s[2:3]
	v_cndmask_b32_e64 v1, v116, v118, s[2:3]
	v_cndmask_b32_e64 v2, v119, v117, s[2:3]
	v_cndmask_b32_e64 v3, v117, v119, s[2:3]
	v_add_u32_dpp v0, v1, v0 row_half_mirror row_mask:0xf bank_mask:0xf bound_ctrl:1
	v_mov_b32_e32 v9, 0
	v_add_u32_dpp v1, v3, v2 row_half_mirror row_mask:0xf bank_mask:0xf bound_ctrl:1
	v_cndmask_b32_e64 v2, v1, v0, s[4:5]
	v_cndmask_b32_e64 v0, v0, v1, s[4:5]
	v_mov_b32_e32 v12, 0
	v_mov_b32_e32 v14, 0
	v_add_u32_dpp v0, v0, v2 quad_perm:[2,3,0,1] row_mask:0xf bank_mask:0xf bound_ctrl:1
	ds_read2st64_b32 v[4:5], v96 offset0:12 offset1:13
	s_waitcnt vmcnt(13)
; __device__ __forceinline__ float row16_sum(float v) { v += dppf<0xB1>(v); v += dppf<0x4E>(v); v += dppf<0x141>(v); v += dppf<0x140>(v); return v; }
; __device__ __forceinline__ float row16_max(float v) { v = fmaxf(v, dppf<0xB1>(v)); v = fmaxf(v, dppf<0x4E>(v)); v = fmaxf(v, dppf<0x141>(v)); v = fmaxf(v, dppf<0x140>(v)); return v; }
; #define LAS __attribute__((address_space(3)))
; __device__ __forceinline__ void peer_block(int tok0, float* X1, const unsigned short* X1B, const int* TKI, const float* TKS, __amdgpu_buffer_rsrc_t U8r, __amdgpu_buffer_rsrc_t V6, const float* USC, const float* VSC,
;                                            const float* finw, pw_ptr L, int lane) {
;     ...
; #pragma unroll
;     for (int t = 0; t < PT; ++t) {
;         const size_t tk = (size_t)(tok0 + t);
;         const float r = *(const LAS float*)(L + PW_R + t * 8), rx = *(const LAS float*)(L + PW_R + t * 8 + 4);
;         const int i0 = *(const LAS int*)(L + PW_REC + t * 512 + lane * 4), i1 = *(const LAS int*)(L + PW_REC + t * 512 + 256 + lane * 4);
;         const size_t rk0 = ((size_t)(lane >> 4) * M + tk) * 16 + (lane & 15), rk1 = rk0 + (size_t)4 * M * 16;
;         const float s0 = TKS[rk0] * r, s1 = TKS[rk1] * r;
;         const float e0 = __expf(s0 - row16_max(s0)), e1 = __expf(s1 - row16_max(s1));
;         const float g0 = e0 / row16_sum(e0), g1 = e1 / row16_sum(e1);
;         const f32x2c sc0 = *(const f32x2c*)(USC + 2 * i0), sc1 = *(const f32x2c*)(USC + 2 * i1);
;         const float a0 = (float)*(const LAS int*)(L + PW_ACT + t * 512 + lane * 4) * rx * sc0.x, a1 = (float)*(const LAS int*)(L + PW_ACT + t * 512 + 256 + lane * 4) * rx * sc1.x;
;         const float w0 = g0 * 0.5f * a0 * (1.0f + erff(a0 * 0.70710678118654752f)) * sc0.y, w1 = g1 * 0.5f * a1 * (1.0f + erff(a1 * 0.70710678118654752f)) * sc1.y;
	v_dot4c_i32_i8_e32 v120, v16, v62
	s_waitcnt vmcnt(12)
	v_dot4c_i32_i8_e32 v121, v20, v62
	s_waitcnt vmcnt(11)
	v_dot4c_i32_i8_e32 v122, v24, v62
	s_waitcnt vmcnt(10)
	v_dot4c_i32_i8_e32 v123, v28, v62
	v_dot4c_i32_i8_e32 v120, v17, v63
	v_dot4c_i32_i8_e32 v121, v21, v63
	v_dot4c_i32_i8_e32 v122, v25, v63
	v_dot4c_i32_i8_e32 v123, v29, v63
	v_dot4c_i32_i8_e32 v120, v18, v64
	v_dot4c_i32_i8_e32 v121, v22, v64
	v_dot4c_i32_i8_e32 v122, v26, v64
	v_dot4c_i32_i8_e32 v123, v30, v64
	v_dot4c_i32_i8_e32 v120, v19, v65
	v_dot4c_i32_i8_e32 v121, v23, v65
	v_dot4c_i32_i8_e32 v122, v27, v65
	v_dot4c_i32_i8_e32 v123, v31, v65
	v_add_u32_dpp v6, v0, v0 quad_perm:[1,0,3,2] row_mask:0xf bank_mask:0xf bound_ctrl:1
	s_waitcnt vmcnt(9)
	v_dot4c_i32_i8_e32 v124, v50, v62
	v_cndmask_b32_e64 v0, v122, v120, s[2:3]
	v_cndmask_b32_e64 v1, v120, v122, s[2:3]
	v_cndmask_b32_e64 v2, v123, v121, s[2:3]
	v_cndmask_b32_e64 v3, v121, v123, s[2:3]
	v_add_u32_dpp v0, v1, v0 row_half_mirror row_mask:0xf bank_mask:0xf bound_ctrl:1
	v_dot4c_i32_i8_e32 v124, v51, v63
	v_add_u32_dpp v1, v3, v2 row_half_mirror row_mask:0xf bank_mask:0xf bound_ctrl:1
	v_cndmask_b32_e64 v2, v1, v0, s[4:5]
	v_cndmask_b32_e64 v0, v0, v1, s[4:5]
	v_mov_b32_e32 v1, 0
	s_waitcnt vmcnt(7)
	v_dot4c_i32_i8_e32 v1, v58, v62
	v_add_u32_dpp v0, v0, v2 quad_perm:[2,3,0,1] row_mask:0xf bank_mask:0xf bound_ctrl:1
	v_mov_b32_e32 v2, 0
	v_dot4c_i32_i8_e32 v1, v59, v63
	v_add_u32_dpp v10, v0, v0 quad_perm:[1,0,3,2] row_mask:0xf bank_mask:0xf bound_ctrl:1
	v_mov_b32_e32 v0, 0
	v_dot4c_i32_i8_e32 v0, v54, v62
	s_waitcnt vmcnt(6)
	v_dot4c_i32_i8_e32 v2, v46, v62
	v_dot4c_i32_i8_e32 v124, v52, v64
	v_dot4c_i32_i8_e32 v0, v55, v63
	v_dot4c_i32_i8_e32 v1, v60, v64
	v_dot4c_i32_i8_e32 v2, v47, v63
	v_dot4c_i32_i8_e32 v124, v53, v65
	v_dot4c_i32_i8_e32 v0, v56, v64
	v_dot4c_i32_i8_e32 v1, v61, v65
	v_dot4c_i32_i8_e32 v2, v48, v64
	v_dot4c_i32_i8_e32 v0, v57, v65
	v_dot4c_i32_i8_e32 v2, v49, v65
	v_cndmask_b32_e64 v3, v1, v124, s[2:3]
	v_cndmask_b32_e64 v1, v124, v1, s[2:3]
	s_waitcnt vmcnt(5)
	v_dot4c_i32_i8_e32 v8, v66, v62
	s_waitcnt vmcnt(4)
	v_dot4c_i32_i8_e32 v9, v104, v62
	v_add_u32_dpp v1, v1, v3 row_half_mirror row_mask:0xf bank_mask:0xf bound_ctrl:1
	v_cndmask_b32_e64 v3, v2, v0, s[2:3]
	v_cndmask_b32_e64 v0, v0, v2, s[2:3]
	s_waitcnt vmcnt(3)
	v_dot4c_i32_i8_e32 v12, v108, v62
	s_waitcnt vmcnt(2)
	v_dot4c_i32_i8_e32 v14, v112, v62
	v_add_u32_dpp v0, v0, v3 row_half_mirror row_mask:0xf bank_mask:0xf bound_ctrl:1
	v_cndmask_b32_e64 v2, v0, v1, s[4:5]
	v_cndmask_b32_e64 v0, v1, v0, s[4:5]
	v_dot4c_i32_i8_e32 v8, v67, v63
	v_dot4c_i32_i8_e32 v9, v105, v63
	v_add_u32_dpp v0, v0, v2 quad_perm:[2,3,0,1] row_mask:0xf bank_mask:0xf bound_ctrl:1
	ds_read2st64_b32 v[2:3], v96 offset1:1
	v_dot4c_i32_i8_e32 v12, v109, v63
	v_add_u32_dpp v7, v0, v0 quad_perm:[1,0,3,2] row_mask:0xf bank_mask:0xf bound_ctrl:1
	v_dot4c_i32_i8_e32 v14, v113, v63
	v_dot4c_i32_i8_e32 v8, v68, v64
	s_waitcnt lgkmcnt(0)
	v_lshlrev_b32_e32 v0, 1, v2
	v_ashrrev_i32_e32 v1, 31, v0
	v_lshl_add_u64 v[0:1], v[0:1], 2, s[34:35]
	global_load_dwordx2 v[0:1], v[0:1], off
	v_lshlrev_b32_e32 v2, 1, v3
	v_ashrrev_i32_e32 v3, 31, v2
	v_lshl_add_u64 v[2:3], v[2:3], 2, s[34:35]
	global_load_dwordx2 v[2:3], v[2:3], off
	v_dot4c_i32_i8_e32 v9, v106, v64
	v_dot4c_i32_i8_e32 v12, v110, v64
	v_dot4c_i32_i8_e32 v14, v114, v64
	v_dot4c_i32_i8_e32 v8, v69, v65
	v_dot4c_i32_i8_e32 v9, v107, v65
	v_dot4c_i32_i8_e32 v12, v111, v65
	v_dot4c_i32_i8_e32 v14, v115, v65
	s_nop 1
	v_cndmask_b32_e64 v15, v12, v8, s[2:3]
	v_cndmask_b32_e64 v8, v8, v12, s[2:3]
	v_cndmask_b32_e64 v12, v14, v9, s[2:3]
	v_cndmask_b32_e64 v9, v9, v14, s[2:3]
	v_add_u32_dpp v8, v8, v15 row_half_mirror row_mask:0xf bank_mask:0xf bound_ctrl:1
	v_add_u32_e32 v14, 0x1400, v100
	v_add_u32_dpp v9, v9, v12 row_half_mirror row_mask:0xf bank_mask:0xf bound_ctrl:1
	v_cndmask_b32_e64 v12, v9, v8, s[4:5]
	v_cndmask_b32_e64 v8, v8, v9, s[4:5]
	v_cndmask_b32_e64 v15, v7, v6, s[6:7]
	v_mov_b32_e32 v6, s33
	v_add_u32_dpp v12, v8, v12 quad_perm:[2,3,0,1] row_mask:0xf bank_mask:0xf bound_ctrl:1
	ds_read2_b32 v[8:9], v14 offset0:128 offset1:132
	ds_read_b64 v[6:7], v6 offset:6144
	v_add_u32_dpp v12, v12, v12 quad_perm:[1,0,3,2] row_mask:0xf bank_mask:0xf bound_ctrl:1
	v_cndmask_b32_e64 v10, v12, v10, s[6:7]
	s_waitcnt lgkmcnt(1)
	v_add_u32_e32 v8, v8, v15
	v_add_u32_e32 v9, v9, v10
	ds_write2_b32 v14, v8, v9 offset0:128 offset1:132
	s_waitcnt vmcnt(3) lgkmcnt(1)
	v_mul_f32_e32 v8, v6, v11
	s_waitcnt vmcnt(2)
	v_mul_f32_e32 v9, v6, v13
	v_mov_b32_dpp v10, v8 quad_perm:[1,0,3,2] row_mask:0xf bank_mask:0xf bound_ctrl:1
	v_max_f32_e32 v10, v10, v10
	v_max_f32_e32 v8, v8, v10
	s_nop 1
	v_mov_b32_dpp v10, v8 quad_perm:[2,3,0,1] row_mask:0xf bank_mask:0xf bound_ctrl:1
	v_max_f32_e32 v10, v10, v10
	v_max_f32_e32 v8, v8, v10
	s_nop 1
	v_mov_b32_dpp v10, v8 row_half_mirror row_mask:0xf bank_mask:0xf bound_ctrl:1
	v_max_f32_e32 v10, v10, v10
	v_max_f32_e32 v8, v8, v10
	s_nop 1
	v_mov_b32_dpp v10, v8 row_mirror row_mask:0xf bank_mask:0xf bound_ctrl:1
	v_max_f32_e32 v10, v10, v10
	v_max_f32_e32 v8, v8, v10
	v_fma_f32 v8, v6, v11, -v8
	v_mul_f32_e32 v8, 0x3fb8aa3b, v8
	v_exp_f32_e32 v12, v8
	v_cvt_f32_i32_e32 v10, v4
	v_mov_b32_dpp v8, v9 quad_perm:[1,0,3,2] row_mask:0xf bank_mask:0xf bound_ctrl:1
	v_max_f32_e32 v8, v8, v8
	v_max_f32_e32 v8, v9, v8
	v_mul_f32_e32 v10, v7, v10
	s_waitcnt vmcnt(1)
	v_mul_f32_e32 v0, v0, v10
	v_mov_b32_dpp v9, v8 quad_perm:[2,3,0,1] row_mask:0xf bank_mask:0xf bound_ctrl:1
	v_max_f32_e32 v9, v9, v9
	v_max_f32_e32 v8, v8, v9
	v_mul_f32_e32 v10, 0x3f3504f3, v0
	v_cmp_nlt_f32_e64 s[10:11], |v10|, 1.0
	v_mov_b32_dpp v9, v8 row_half_mirror row_mask:0xf bank_mask:0xf bound_ctrl:1
	v_max_f32_e32 v9, v9, v9
	v_max_f32_e32 v8, v8, v9
	s_nop 1
	v_mov_b32_dpp v9, v8 row_mirror row_mask:0xf bank_mask:0xf bound_ctrl:1
	v_max_f32_e32 v9, v9, v9
	v_max_f32_e32 v8, v8, v9
	v_fma_f32 v6, v6, v13, -v8
	v_mul_f32_e32 v6, 0x3fb8aa3b, v6
	v_exp_f32_e32 v13, v6
	s_nop 0
	v_add_f32_dpp v6, v12, v12 quad_perm:[1,0,3,2] row_mask:0xf bank_mask:0xf bound_ctrl:1
	v_add_f32_dpp v9, v13, v13 quad_perm:[1,0,3,2] row_mask:0xf bank_mask:0xf bound_ctrl:1
	s_nop 0
	v_add_f32_dpp v6, v6, v6 quad_perm:[2,3,0,1] row_mask:0xf bank_mask:0xf bound_ctrl:1
	v_add_f32_dpp v4, v9, v9 quad_perm:[2,3,0,1] row_mask:0xf bank_mask:0xf bound_ctrl:1
	s_nop 0
	v_add_f32_dpp v6, v6, v6 row_half_mirror row_mask:0xf bank_mask:0xf bound_ctrl:1
	v_add_f32_dpp v4, v4, v4 row_half_mirror row_mask:0xf bank_mask:0xf bound_ctrl:1
	s_nop 0
	v_mov_b32_dpp v8, v6 row_mirror row_mask:0xf bank_mask:0xf bound_ctrl:1
	v_mov_b32_dpp v9, v4 row_mirror row_mask:0xf bank_mask:0xf bound_ctrl:1
	s_and_saveexec_b64 s[40:41], s[10:11]
	s_xor_b64 s[10:11], exec, s[40:41]
	s_cbranch_execz .LBB0_695
; __device__ __forceinline__ void peer_block(int tok0, float* X1, const unsigned short* X1B, const int* TKI, const float* TKS, __amdgpu_buffer_rsrc_t U8r, __amdgpu_buffer_rsrc_t V6, const float* USC, const float* VSC,
;                                            const float* finw, pw_ptr L, int lane) {
;     ...
;         const float w0 = g0 * 0.5f * a0 * (1.0f + erff(a0 * 0.70710678118654752f)) * sc0.y, w1 = g1 * 0.5f * a1 * (1.0f + erff(a1 * 0.70710678118654752f)) * sc1.y;
	v_fma_f32 v11, |v10|, s50, v102
	v_fma_f32 v11, |v10|, v11, s51
	v_fma_f32 v11, |v10|, v11, s52
	v_fma_f32 v11, |v10|, v11, s53
	v_fma_f32 v11, |v10|, v11, s54
	v_fma_f32 v11, |v10|, v11, s55
	v_fma_f32 v11, |v10|, v11, |v10|
	v_mul_f32_e32 v14, 0xbfb8aa3b, v11
	v_fma_f32 v15, v11, s56, -v14
	v_rndne_f32_e32 v16, v14
	v_fmac_f32_e32 v15, 0xb2a5705f, v11
	v_sub_f32_e32 v14, v14, v16
	v_add_f32_e32 v14, v14, v15
	v_cvt_i32_f32_e32 v15, v16
	v_exp_f32_e32 v14, v14
	v_cmp_nlt_f32_e32 vcc, s57, v11
	v_ldexp_f32 v14, v14, v15
	s_nop 0
	v_cndmask_b32_e32 v14, 0, v14, vcc
	v_cmp_ngt_f32_e32 vcc, s58, v11
	s_nop 1
	v_cndmask_b32_e32 v11, v103, v14, vcc
	v_sub_f32_e32 v11, 1.0, v11
